# same as v078 plus grid-size guards (LRU software pipelining only when gridDim==256; hand-written P3 grid-stride)
# baseline (speedup 1.0000x reference)
; DI void lru_tile(const Params& p, unsigned char* shm, int c, int nb, const LruPar par) {
;     ...
;         for (int gi = 0; gi < 32; ++gi) {
;             const int G = d == 0 ? gi : 31 - gi; const int rt = G >> 2, qq = G & 3;
;             const f32x2 ah = AG[G * 16 + col];
;             if (qq == q) { carry[rt] = cin; pref[rt] = pa; }
;             cin = fmaf(ah[0], cin, ah[1]); pa *= ah[0];
;         }
;         if (q == 0) AGG[((size_t)d * 128 + c) * 2048 + chg] = (f32x2){pa, cin};
; #pragma unroll
;         for (int rt = 0; rt < 8; ++rt) {
;             const f32x2 cr2 = {carry[rt], carry[rt]}, pf2 = {pref[rt] * 255.f, pref[rt] * 255.f}, half2 = {0.5f, 0.5f};
; #pragma unroll
;             for (int jp = 0; jp < 2; ++jp) {
;                 const f32x2 pc2 = {pc[rt][2 * jp], pc[rt][2 * jp + 1]}, hl2 = {hl[rt][2 * jp], hl[rt][2 * jp + 1]};
;                 const f32x2 hf = pc2 * cr2 + hl2, pq = pc2 * pf2 + half2;
;                 const unsigned q0 = (unsigned)pq[0], q1 = (unsigned)pq[1];
;                 if (d == 0) { hsum[rt][2 * jp] = hf[0]; hsum[rt][2 * jp + 1] = hf[1]; ppk[rt][jp] = q0 | (q1 << 16); }
.LBB0_211:
	s_or_b64 exec, exec, s[60:61]
	v_cndmask_b32_e64 v56, v90, 0, s[10:11]
	v_cndmask_b32_e64 v56, v56, v119, s[4:5]
	v_cndmask_b32_e64 v56, v56, v127, s[6:7]
	v_cndmask_b32_e64 v178, v56, v129, s[8:9]
	v_cndmask_b32_e64 v56, v88, v137, s[10:11]
	v_cndmask_b32_e64 v56, v56, v139, s[4:5]
	v_cndmask_b32_e64 v56, v56, v147, s[6:7]
	v_cndmask_b32_e64 v238, v56, v149, s[8:9]
	v_cndmask_b32_e64 v56, v84, v157, s[10:11]
	v_cndmask_b32_e64 v56, v56, v159, s[4:5]
	v_cndmask_b32_e64 v56, v56, v183, s[6:7]
	v_cndmask_b32_e64 v184, v56, v184, s[8:9]
	v_cndmask_b32_e64 v56, v80, v185, s[10:11]
	v_cndmask_b32_e64 v56, v56, v186, s[4:5]
	v_cndmask_b32_e64 v56, v56, v187, s[6:7]
	v_cndmask_b32_e64 v186, v56, v188, s[8:9]
	v_cndmask_b32_e64 v56, v78, v189, s[10:11]
	v_cndmask_b32_e64 v56, v56, v190, s[4:5]
	v_cndmask_b32_e64 v56, v56, v192, s[6:7]
	v_cndmask_b32_e64 v188, v56, v193, s[8:9]
	v_cndmask_b32_e64 v56, v76, v194, s[10:11]
	v_cndmask_b32_e64 v56, v56, v195, s[4:5]
	v_cndmask_b32_e64 v56, v56, v196, s[6:7]
	v_cndmask_b32_e64 v190, v56, v197, s[8:9]
	v_cndmask_b32_e64 v56, v74, v198, s[10:11]
	v_cndmask_b32_e64 v56, v56, v200, s[4:5]
	v_cndmask_b32_e64 v56, v56, v201, s[6:7]
	v_cndmask_b32_e64 v192, v56, v204, s[8:9]
	v_cndmask_b32_e64 v56, v72, v205, s[10:11]
	v_cndmask_b32_e64 v56, v56, v206, s[4:5]
	v_cndmask_b32_e64 v56, v56, v207, s[6:7]
	v_cndmask_b32_e64 v194, v56, v163, s[8:9]
	v_cndmask_b32_e64 v56, v56, 0, s[8:9]
	v_mul_f32_e32 v196, 0x437f0000, v199
	v_mov_b32_e32 v159, v154
	v_cndmask_b32_e64 v7, v56, v7, s[6:7]
	v_pk_fma_f32 v[56:57], v[158:159], v[196:197], 0.5 op_sel_hi:[1,0,0]
	v_mov_b32_e32 v157, v155
	v_pk_fma_f32 v[154:155], v[150:151], v[196:197], 0.5 op_sel_hi:[1,0,0]
	v_pk_fma_f32 v[150:151], v[150:151], v[194:195], v[152:153] op_sel_hi:[1,0,1]
	v_mul_f32_e32 v152, 0x437f0000, v191
	v_mov_b32_e32 v149, v144
	v_cvt_u32_f32_sdwa v163, v57 dst_sel:WORD_1 dst_unused:UNUSED_PAD src0_sel:DWORD
	v_cvt_u32_f32_e32 v179, v56
	v_pk_fma_f32 v[56:57], v[158:159], v[194:195], v[156:157] op_sel_hi:[1,0,1]
	v_cvt_u32_f32_sdwa v156, v155 dst_sel:WORD_1 dst_unused:UNUSED_PAD src0_sel:DWORD
	v_cvt_u32_f32_e32 v157, v154
	v_pk_fma_f32 v[154:155], v[148:149], v[152:153], 0.5 op_sel_hi:[1,0,0]
	v_mov_b32_e32 v147, v145
	v_cvt_u32_f32_e32 v153, v154
	v_pk_fma_f32 v[144:145], v[148:149], v[192:193], v[146:147] op_sel_hi:[1,0,1]
	v_mov_b32_e32 v139, v134
	v_mov_b32_e32 v137, v135
	v_pk_fma_f32 v[146:147], v[140:141], v[152:153], 0.5 op_sel_hi:[1,0,0]
	v_pk_fma_f32 v[140:141], v[140:141], v[192:193], v[142:143] op_sel_hi:[1,0,1]
	v_mul_f32_e32 v142, 0x437f0000, v182
	v_cvt_u32_f32_sdwa v148, v147 dst_sel:WORD_1 dst_unused:UNUSED_PAD src0_sel:DWORD
	v_cvt_u32_f32_e32 v149, v146
	v_pk_fma_f32 v[146:147], v[138:139], v[142:143], 0.5 op_sel_hi:[1,0,0]
	v_pk_fma_f32 v[134:135], v[138:139], v[190:191], v[136:137] op_sel_hi:[1,0,1]
	v_cvt_u32_f32_e32 v143, v146
	v_mov_b32_e32 v129, v124
	v_mov_b32_e32 v127, v125
	v_pk_fma_f32 v[124:125], v[128:129], v[188:189], v[126:127] op_sel_hi:[1,0,1]
	v_pk_fma_f32 v[136:137], v[130:131], v[142:143], 0.5 op_sel_hi:[1,0,0]
	v_pk_fma_f32 v[130:131], v[130:131], v[190:191], v[132:133] op_sel_hi:[1,0,1]
	v_mul_f32_e32 v132, 0x437f0000, v117
	v_cvt_u32_f32_sdwa v138, v137 dst_sel:WORD_1 dst_unused:UNUSED_PAD src0_sel:DWORD
	v_cvt_u32_f32_e32 v139, v136
	v_pk_fma_f32 v[136:137], v[128:129], v[132:133], 0.5 op_sel_hi:[1,0,0]
	v_mov_b32_e32 v119, v114
	v_cvt_u32_f32_e32 v133, v136
	v_mov_b32_e32 v117, v115
	v_cndmask_b32_e64 v7, v7, v15, s[4:5]
	v_pk_fma_f32 v[114:115], v[118:119], v[186:187], v[116:117] op_sel_hi:[1,0,1]
	v_pk_fma_f32 v[126:127], v[120:121], v[132:133], 0.5 op_sel_hi:[1,0,0]
	v_pk_fma_f32 v[120:121], v[120:121], v[188:189], v[122:123] op_sel_hi:[1,0,1]
	v_mul_f32_e32 v122, 0x437f0000, v109
	v_cvt_u32_f32_sdwa v128, v127 dst_sel:WORD_1 dst_unused:UNUSED_PAD src0_sel:DWORD
	v_cvt_u32_f32_e32 v129, v126
	v_pk_fma_f32 v[126:127], v[118:119], v[122:123], 0.5 op_sel_hi:[1,0,0]
	v_mov_b32_e32 v109, v104
	v_cvt_u32_f32_sdwa v123, v127 dst_sel:WORD_1 dst_unused:UNUSED_PAD src0_sel:DWORD
	v_cndmask_b32_e64 v72, v7, v23, s[10:11]
	v_cndmask_b32_e64 v7, v192, v39, s[8:9]
	v_cndmask_b32_e64 v7, v7, v47, s[6:7]
	v_pk_fma_f32 v[116:117], v[110:111], v[122:123], 0.5 op_sel_hi:[1,0,0]
	v_pk_fma_f32 v[110:111], v[110:111], v[186:187], v[112:113] op_sel_hi:[1,0,1]
	v_mul_f32_e32 v112, 0x437f0000, v107
	v_cvt_u32_f32_sdwa v118, v117 dst_sel:WORD_1 dst_unused:UNUSED_PAD src0_sel:DWORD
	v_cvt_u32_f32_e32 v119, v116
	v_pk_fma_f32 v[116:117], v[108:109], v[112:113], 0.5 op_sel_hi:[1,0,0]
	v_cndmask_b32_e64 v7, v7, v61, s[4:5]
	v_cvt_u32_f32_e32 v113, v116
	v_cndmask_b32_e64 v74, v7, v97, s[10:11]
	v_cndmask_b32_e64 v7, v190, v171, s[8:9]
	v_cndmask_b32_e64 v7, v7, v177, s[6:7]
	v_mov_b32_e32 v107, v105
	v_cndmask_b32_e64 v7, v7, v215, s[4:5]
	v_pk_fma_f32 v[104:105], v[108:109], v[184:185], v[106:107] op_sel_hi:[1,0,1]
	v_pk_fma_f32 v[106:107], v[100:101], v[112:113], 0.5 op_sel_hi:[1,0,0]
	v_pk_fma_f32 v[100:101], v[100:101], v[184:185], v[102:103] op_sel_hi:[1,0,1]
	v_mul_f32_e32 v102, 0x437f0000, v99
	v_mov_b32_e32 v99, v66
	v_cndmask_b32_e64 v76, v7, v216, s[10:11]
	v_cndmask_b32_e64 v7, v188, v217, s[8:9]
	v_cvt_u32_f32_sdwa v108, v107 dst_sel:WORD_1 dst_unused:UNUSED_PAD src0_sel:DWORD
	v_cvt_u32_f32_e32 v109, v106
	v_pk_fma_f32 v[106:107], v[98:99], v[102:103], 0.5 op_sel_hi:[1,0,0]
	v_cndmask_b32_e64 v7, v7, v218, s[6:7]
	v_cvt_u32_f32_e32 v103, v106
	v_cndmask_b32_e64 v7, v7, v219, s[4:5]
	v_cndmask_b32_e64 v78, v7, v220, s[10:11]
	v_cndmask_b32_e64 v7, v186, v221, s[8:9]
	v_cndmask_b32_e64 v7, v7, v222, s[6:7]
; DI unsigned cvtpk(float lo, float hi) { unsigned r; asm volatile("v_cvt_pk_bf16_f32 %0, %1, %2" : "=v"(r) : "v"(lo), "v"(hi)); return r; }
; DI void lru_tile(const Params& p, unsigned char* shm, int c, int nb, const LruPar par) {
;     ...
;         for (int rt = 0; rt < 8; ++rt) {
;             const f32x2 cr2 = {carry[rt], carry[rt]}, pf2 = {pref[rt] * 255.f, pref[rt] * 255.f}, half2 = {0.5f, 0.5f};
; #pragma unroll
;             for (int jp = 0; jp < 2; ++jp) {
;                 const f32x2 pc2 = {pc[rt][2 * jp], pc[rt][2 * jp + 1]}, hl2 = {hl[rt][2 * jp], hl[rt][2 * jp + 1]};
;                 const f32x2 hf = pc2 * cr2 + hl2, pq = pc2 * pf2 + half2;
;                 const unsigned q0 = (unsigned)pq[0], q1 = (unsigned)pq[1];
;                 if (d == 0) { hsum[rt][2 * jp] = hf[0]; hsum[rt][2 * jp + 1] = hf[1]; ppk[rt][jp] = q0 | (q1 << 16); }
;                 else {
;                     const int lo = (rt * 16 + 4 * q + 2 * jp) * LDU + chl;
;                     const unsigned w = cvtpk(hsum[rt][2 * jp] + hf[0], hsum[rt][2 * jp + 1] + hf[1]);
;                     OS[lo] = (unsigned short)(w & 0xffffu); OS[lo + LDU] = (unsigned short)(w >> 16);
;                     const unsigned pw = ppk[rt][jp] | (q0 << 8) | (q1 << 24);
;                     PS[lo] = (unsigned short)(pw & 0xffffu); PS[lo + LDU] = (unsigned short)(pw >> 16);
;                 }
	v_mov_b32_e32 v97, v67
	v_cndmask_b32_e64 v7, v7, v223, s[4:5]
	v_pk_fma_f32 v[66:67], v[98:99], v[238:239], v[96:97] op_sel_hi:[1,0,1]
	v_pk_fma_f32 v[96:97], v[62:63], v[102:103], 0.5 op_sel_hi:[1,0,0]
	v_pk_fma_f32 v[62:63], v[62:63], v[238:239], v[64:65] op_sel_hi:[1,0,1]
	v_mul_f32_e32 v64, 0x437f0000, v181
	v_mov_b32_e32 v61, v54
	v_cndmask_b32_e64 v80, v7, v224, s[10:11]
	v_cndmask_b32_e64 v7, v184, v225, s[8:9]
	v_cvt_u32_f32_sdwa v98, v97 dst_sel:WORD_1 dst_unused:UNUSED_PAD src0_sel:DWORD
	v_cvt_u32_f32_e32 v99, v96
	v_pk_fma_f32 v[96:97], v[60:61], v[64:65], 0.5 op_sel_hi:[1,0,0]
	v_cndmask_b32_e64 v7, v7, v226, s[6:7]
	v_cvt_u32_f32_sdwa v65, v97 dst_sel:WORD_1 dst_unused:UNUSED_PAD src0_sel:DWORD
	v_cndmask_b32_e64 v7, v7, v227, s[4:5]
	v_cndmask_b32_e64 v84, v7, v228, s[10:11]
	v_cndmask_b32_e64 v7, v238, v229, s[8:9]
	v_cndmask_b32_e64 v7, v7, v230, s[6:7]
	v_mov_b32_e32 v59, v55
	v_cndmask_b32_e64 v7, v7, v231, s[4:5]
	v_pk_fma_f32 v[54:55], v[60:61], v[178:179], v[58:59] op_sel_hi:[1,0,1]
	v_pk_fma_f32 v[58:59], v[50:51], v[64:65], 0.5 op_sel_hi:[1,0,0]
	v_pk_fma_f32 v[50:51], v[50:51], v[178:179], v[52:53] op_sel_hi:[1,0,1]
	v_mul_f32_e32 v52, 0x437f0000, v31
	v_mov_b32_e32 v171, v49
	v_cndmask_b32_e64 v88, v7, v232, s[10:11]
	v_cndmask_b32_e64 v7, v178, v233, s[8:9]
	v_cvt_u32_f32_sdwa v60, v59 dst_sel:WORD_1 dst_unused:UNUSED_PAD src0_sel:DWORD
	v_cvt_u32_f32_e32 v61, v58
	v_pk_fma_f32 v[58:59], v[170:171], v[52:53], 0.5 op_sel_hi:[1,0,0]
	v_cndmask_b32_e64 v7, v7, v234, s[6:7]
	v_cvt_u32_f32_e32 v49, v58
	v_cndmask_b32_e64 v7, v7, v235, s[4:5]
	v_cndmask_b32_e64 v90, v7, v236, s[10:11]
	v_cvt_u32_f32_e32 v31, v59
	v_pk_fma_f32 v[58:59], v[170:171], v[90:91], v[168:169] op_sel_hi:[1,0,1]
	v_add_lshl_u32 v53, v48, v95, 1
	v_pk_add_f32 v[50:51], v[50:51], v[58:59]
	v_lshlrev_b32_e32 v48, 8, v49
	v_cvt_pk_bf16_f32 v50, v50, v51
	v_add_u32_e32 v58, s68, v53
	v_or3_b32 v48, v60, v61, v48
	ds_write_b16 v58, v50
	ds_write_b16_d16_hi v58, v50 offset:272
	v_lshl_or_b32 v31, v31, 24, v48
	ds_write_b16 v68, v48 offset:34816
	ds_write_b16_d16_hi v68, v31 offset:35088
	v_pk_fma_f32 v[48:49], v[160:161], v[52:53], 0.5 op_sel_hi:[1,0,0]
	v_cvt_u32_f32_e32 v96, v96
	v_cvt_u32_f32_e32 v50, v48
	v_cvt_u32_f32_e32 v31, v49
	v_pk_fma_f32 v[48:49], v[160:161], v[90:91], v[166:167] op_sel_hi:[1,0,1]
	v_cvt_u32_f32_sdwa v7, v155 dst_sel:WORD_1 dst_unused:UNUSED_PAD src0_sel:DWORD
	v_pk_add_f32 v[48:49], v[54:55], v[48:49]
	v_cvt_u32_f32_sdwa v15, v147 dst_sel:WORD_1 dst_unused:UNUSED_PAD src0_sel:DWORD
	v_cvt_pk_bf16_f32 v48, v48, v49
	ds_write_b16 v58, v48 offset:544
	ds_write_b16_d16_hi v58, v48 offset:816
	v_lshlrev_b32_e32 v48, 8, v50
	v_or3_b32 v48, v65, v96, v48
	v_cvt_u32_f32_sdwa v23, v137 dst_sel:WORD_1 dst_unused:UNUSED_PAD src0_sel:DWORD
	v_cvt_u32_f32_e32 v126, v126
	v_cvt_u32_f32_sdwa v39, v117 dst_sel:WORD_1 dst_unused:UNUSED_PAD src0_sel:DWORD
	v_cvt_u32_f32_sdwa v47, v107 dst_sel:WORD_1 dst_unused:UNUSED_PAD src0_sel:DWORD
	v_lshl_or_b32 v31, v31, 24, v48
	ds_write_b16 v68, v48 offset:35360
	ds_write_b16_d16_hi v68, v31 offset:35632
	v_mul_f32_e32 v48, 0x437f0000, v162
	v_mov_b32_e32 v177, v208
	v_pk_fma_f32 v[50:51], v[176:177], v[48:49], 0.5 op_sel_hi:[1,0,0]
	s_nop 0
	v_cvt_u32_f32_e32 v49, v50
	v_cvt_u32_f32_e32 v31, v51
	v_pk_fma_f32 v[50:51], v[176:177], v[88:89], v[174:175] op_sel_hi:[1,0,1]
	v_lshlrev_b32_e32 v49, 8, v49
	v_pk_add_f32 v[50:51], v[62:63], v[50:51]
	v_or3_b32 v49, v98, v99, v49
	v_cvt_pk_bf16_f32 v50, v50, v51
	ds_write_b16 v58, v50 offset:4352
	ds_write_b16_d16_hi v58, v50 offset:4624
	v_lshl_or_b32 v31, v31, 24, v49
	ds_write_b16 v68, v49 offset:39168
	ds_write_b16_d16_hi v68, v31 offset:39440
	v_pk_fma_f32 v[48:49], v[164:165], v[48:49], 0.5 op_sel_hi:[1,0,0]
	s_nop 0
	v_cvt_u32_f32_e32 v50, v48
	v_cvt_u32_f32_e32 v31, v49
	v_pk_fma_f32 v[48:49], v[164:165], v[88:89], v[172:173] op_sel_hi:[1,0,1]
	s_nop 0
	v_pk_add_f32 v[48:49], v[66:67], v[48:49]
	s_nop 0
	v_cvt_pk_bf16_f32 v48, v48, v49
	ds_write_b16 v58, v48 offset:4896
	ds_write_b16_d16_hi v58, v48 offset:5168
	v_lshlrev_b32_e32 v48, 8, v50
	v_or3_b32 v47, v47, v103, v48
	v_lshl_or_b32 v31, v31, 24, v47
	ds_write_b16 v68, v47 offset:39712
	ds_write_b16_d16_hi v68, v31 offset:39984
	v_mul_f32_e32 v48, 0x437f0000, v91
	v_mov_b32_e32 v47, v209
	v_pk_fma_f32 v[50:51], v[46:47], v[48:49], 0.5 op_sel_hi:[1,0,0]
	v_pk_fma_f32 v[44:45], v[46:47], v[84:85], v[44:45] op_sel_hi:[1,0,1]
	v_cvt_u32_f32_e32 v49, v50
	v_cvt_u32_f32_e32 v31, v51
	v_pk_add_f32 v[44:45], v[100:101], v[44:45]
	v_pk_fma_f32 v[40:41], v[42:43], v[84:85], v[40:41] op_sel_hi:[1,0,1]
	v_cvt_pk_bf16_f32 v44, v44, v45
	ds_write_b16 v58, v44 offset:8704
	ds_write_b16_d16_hi v58, v44 offset:8976
	v_lshlrev_b32_e32 v44, 8, v49
	v_or3_b32 v44, v108, v109, v44
	v_lshl_or_b32 v31, v31, 24, v44
	ds_write_b16 v68, v44 offset:43520
	ds_write_b16_d16_hi v68, v31 offset:43792
	v_pk_fma_f32 v[44:45], v[42:43], v[48:49], 0.5 op_sel_hi:[1,0,0]
	v_pk_add_f32 v[40:41], v[104:105], v[40:41]
	v_cvt_u32_f32_e32 v44, v44
	v_cvt_u32_f32_e32 v31, v45
	v_cvt_pk_bf16_f32 v40, v40, v41
	ds_write_b16 v58, v40 offset:9248
	ds_write_b16_d16_hi v58, v40 offset:9520
	v_lshlrev_b32_e32 v40, 8, v44
	v_or3_b32 v39, v39, v113, v40
	v_lshl_or_b32 v31, v31, 24, v39
	ds_write_b16 v68, v39 offset:44064
	ds_write_b16_d16_hi v68, v31 offset:44336
	v_mul_f32_e32 v40, 0x437f0000, v89
	v_mov_b32_e32 v39, v210
	v_pk_fma_f32 v[42:43], v[38:39], v[40:41], 0.5 op_sel_hi:[1,0,0]
	v_pk_fma_f32 v[36:37], v[38:39], v[80:81], v[36:37] op_sel_hi:[1,0,1]
	v_cvt_u32_f32_e32 v41, v42
	v_cvt_u32_f32_e32 v31, v43
	v_pk_add_f32 v[36:37], v[110:111], v[36:37]
; DI unsigned cvtpk(float lo, float hi) { unsigned r; asm volatile("v_cvt_pk_bf16_f32 %0, %1, %2" : "=v"(r) : "v"(lo), "v"(hi)); return r; }
; DI float bflo(unsigned w) { return __uint_as_float(w << 16); }
; DI float bfhi(unsigned w) { return __uint_as_float(w & 0xffff0000u); }
; DI void lru_tile(const Params& p, unsigned char* shm, int c, int nb, const LruPar par) {
;     ...
;         const int cgp = tid & 15, rg = tid >> 4, ch = nb * 128 + cgp * 8;
;         const float* cw = p.in[3]; const float* cb = p.in[4];
;         float w[4][8], bias[8];
; #pragma unroll
;         for (int tp = 0; tp < 4; ++tp) { const f32x4 a = *(const f32x4*)(cw + tp * 2048 + ch), b = *(const f32x4*)(cw + tp * 2048 + ch + 4);
;             w[tp][0] = a[0]; w[tp][1] = a[1]; w[tp][2] = a[2]; w[tp][3] = a[3]; w[tp][4] = b[0]; w[tp][5] = b[1]; w[tp][6] = b[2]; w[tp][7] = b[3]; }
;         { const f32x4 a = *(const f32x4*)(cb + ch), b = *(const f32x4*)(cb + ch + 4);
;             bias[0] = a[0]; bias[1] = a[1]; bias[2] = a[2]; bias[3] = a[3]; bias[4] = b[0]; bias[5] = b[1]; bias[6] = b[2]; bias[7] = b[3]; }
;         float xr[7][8];
; #pragma unroll
;         for (int k = 0; k < 7; ++k) { const int t = c * 128 + rg * 4 - 2 + k;
;             u32x4 v = {0u, 0u, 0u, 0u};
;             if (t >= 0 && t < S) v = *(const u32x4*)(ZU + (size_t)(nb >> 1) * S * 256 + (size_t)t * 256 + (nb & 1) * 128 + cgp * 8);
; #pragma unroll
;             for (int i = 0; i < 4; ++i) { xr[k][2 * i] = bflo(v[i]); xr[k][2 * i + 1] = bfhi(v[i]); } }
;     ...
;                 else {
;                     const int lo = (rt * 16 + 4 * q + 2 * jp) * LDU + chl;
;                     const unsigned w = cvtpk(hsum[rt][2 * jp] + hf[0], hsum[rt][2 * jp + 1] + hf[1]);
;                     OS[lo] = (unsigned short)(w & 0xffffu); OS[lo + LDU] = (unsigned short)(w >> 16);
;                     const unsigned pw = ppk[rt][jp] | (q0 << 8) | (q1 << 24);
;                     PS[lo] = (unsigned short)(pw & 0xffffu); PS[lo + LDU] = (unsigned short)(pw >> 16);
;                 }
	v_pk_fma_f32 v[32:33], v[34:35], v[80:81], v[32:33] op_sel_hi:[1,0,1]
	v_cvt_pk_bf16_f32 v36, v36, v37
	ds_write_b16 v58, v36 offset:13056
	ds_write_b16_d16_hi v58, v36 offset:13328
	v_lshlrev_b32_e32 v36, 8, v41
	v_or3_b32 v36, v118, v119, v36
	v_lshl_or_b32 v31, v31, 24, v36
	ds_write_b16 v68, v36 offset:47872
	ds_write_b16_d16_hi v68, v31 offset:48144
	v_pk_fma_f32 v[36:37], v[34:35], v[40:41], 0.5 op_sel_hi:[1,0,0]
	v_pk_add_f32 v[32:33], v[114:115], v[32:33]
	v_cvt_u32_f32_e32 v36, v36
	v_cvt_u32_f32_e32 v31, v37
	v_cvt_pk_bf16_f32 v32, v32, v33
	ds_write_b16 v58, v32 offset:13600
	ds_write_b16_d16_hi v58, v32 offset:13872
	v_lshlrev_b32_e32 v32, 8, v36
	v_or3_b32 v32, v123, v126, v32
	v_lshl_or_b32 v31, v31, 24, v32
	ds_write_b16 v68, v32 offset:48416
	ds_write_b16_d16_hi v68, v31 offset:48688
	v_mul_f32_e32 v32, 0x437f0000, v85
	v_mov_b32_e32 v31, v211
	v_pk_fma_f32 v[34:35], v[30:31], v[32:33], 0.5 op_sel_hi:[1,0,0]
	v_pk_fma_f32 v[28:29], v[30:31], v[78:79], v[28:29] op_sel_hi:[1,0,1]
	v_cvt_u32_f32_e32 v34, v34
	v_cvt_u32_f32_e32 v33, v35
	v_pk_add_f32 v[28:29], v[120:121], v[28:29]
	v_pk_fma_f32 v[24:25], v[26:27], v[78:79], v[24:25] op_sel_hi:[1,0,1]
	v_cvt_pk_bf16_f32 v28, v28, v29
	ds_write_b16 v58, v28 offset:17408
	ds_write_b16_d16_hi v58, v28 offset:17680
	v_lshlrev_b32_e32 v28, 8, v34
	v_or3_b32 v28, v128, v129, v28
	v_lshl_or_b32 v29, v33, 24, v28
	ds_write_b16 v68, v28 offset:52224
	ds_write_b16_d16_hi v68, v29 offset:52496
	v_pk_fma_f32 v[28:29], v[26:27], v[32:33], 0.5 op_sel_hi:[1,0,0]
	v_pk_add_f32 v[24:25], v[124:125], v[24:25]
	v_cvt_u32_f32_e32 v28, v28
	v_cvt_u32_f32_e32 v29, v29
	v_cvt_pk_bf16_f32 v24, v24, v25
	ds_write_b16 v58, v24 offset:17952
	ds_write_b16_d16_hi v58, v24 offset:18224
	v_lshlrev_b32_e32 v24, 8, v28
	v_or3_b32 v23, v23, v133, v24
	v_lshl_or_b32 v24, v29, 24, v23
	ds_write_b16 v68, v23 offset:52768
	ds_write_b16_d16_hi v68, v24 offset:53040
	v_mul_f32_e32 v24, 0x437f0000, v81
	v_mov_b32_e32 v23, v212
	v_pk_fma_f32 v[26:27], v[22:23], v[24:25], 0.5 op_sel_hi:[1,0,0]
	v_pk_fma_f32 v[20:21], v[22:23], v[76:77], v[20:21] op_sel_hi:[1,0,1]
	v_cvt_u32_f32_e32 v26, v26
	v_cvt_u32_f32_e32 v25, v27
	v_pk_add_f32 v[20:21], v[130:131], v[20:21]
	v_pk_fma_f32 v[16:17], v[18:19], v[76:77], v[16:17] op_sel_hi:[1,0,1]
	v_cvt_pk_bf16_f32 v20, v20, v21
	ds_write_b16 v58, v20 offset:21760
	ds_write_b16_d16_hi v58, v20 offset:22032
	v_lshlrev_b32_e32 v20, 8, v26
	v_or3_b32 v20, v138, v139, v20
	v_lshl_or_b32 v21, v25, 24, v20
	ds_write_b16 v68, v20 offset:56576
	ds_write_b16_d16_hi v68, v21 offset:56848
	v_pk_fma_f32 v[20:21], v[18:19], v[24:25], 0.5 op_sel_hi:[1,0,0]
	v_pk_add_f32 v[16:17], v[134:135], v[16:17]
	v_cvt_u32_f32_e32 v20, v20
	v_cvt_u32_f32_e32 v21, v21
	v_cvt_pk_bf16_f32 v16, v16, v17
	ds_write_b16 v58, v16 offset:22304
	ds_write_b16_d16_hi v58, v16 offset:22576
	v_lshlrev_b32_e32 v16, 8, v20
	v_or3_b32 v15, v15, v143, v16
	v_lshl_or_b32 v16, v21, 24, v15
	ds_write_b16 v68, v15 offset:57120
	ds_write_b16_d16_hi v68, v16 offset:57392
	v_mul_f32_e32 v16, 0x437f0000, v79
	v_mov_b32_e32 v15, v213
	v_pk_fma_f32 v[18:19], v[14:15], v[16:17], 0.5 op_sel_hi:[1,0,0]
	v_pk_fma_f32 v[12:13], v[14:15], v[74:75], v[12:13] op_sel_hi:[1,0,1]
	v_cvt_u32_f32_e32 v18, v18
	v_cvt_u32_f32_e32 v17, v19
	v_pk_add_f32 v[12:13], v[140:141], v[12:13]
	v_pk_fma_f32 v[8:9], v[10:11], v[74:75], v[8:9] op_sel_hi:[1,0,1]
	v_cvt_pk_bf16_f32 v12, v12, v13
	ds_write_b16 v58, v12 offset:26112
	ds_write_b16_d16_hi v58, v12 offset:26384
	v_lshlrev_b32_e32 v12, 8, v18
	v_or3_b32 v12, v148, v149, v12
	v_lshl_or_b32 v13, v17, 24, v12
	ds_write_b16 v68, v12 offset:60928
	ds_write_b16_d16_hi v68, v13 offset:61200
	v_pk_fma_f32 v[12:13], v[10:11], v[16:17], 0.5 op_sel_hi:[1,0,0]
	v_pk_add_f32 v[8:9], v[144:145], v[8:9]
	v_cvt_u32_f32_e32 v12, v12
	v_cvt_u32_f32_e32 v13, v13
	v_cvt_pk_bf16_f32 v8, v8, v9
	ds_write_b16 v58, v8 offset:26656
	ds_write_b16_d16_hi v58, v8 offset:26928
	v_lshlrev_b32_e32 v8, 8, v12
	v_or3_b32 v7, v7, v153, v8
	v_lshl_or_b32 v8, v13, 24, v7
	ds_write_b16 v68, v7 offset:61472
	ds_write_b16_d16_hi v68, v8 offset:61744
	v_mul_f32_e32 v8, 0x437f0000, v77
	v_mov_b32_e32 v7, v214
	v_pk_fma_f32 v[10:11], v[6:7], v[8:9], 0.5 op_sel_hi:[1,0,0]
	v_pk_fma_f32 v[4:5], v[6:7], v[72:73], v[4:5] op_sel_hi:[1,0,1]
	v_cvt_u32_f32_e32 v10, v10
	v_cvt_u32_f32_e32 v9, v11
	v_pk_add_f32 v[4:5], v[150:151], v[4:5]
	v_pk_fma_f32 v[0:1], v[2:3], v[72:73], v[0:1] op_sel_hi:[1,0,1]
	v_cvt_pk_bf16_f32 v4, v4, v5
	ds_write_b16 v58, v4 offset:30464
	ds_write_b16_d16_hi v58, v4 offset:30736
	v_lshlrev_b32_e32 v4, 8, v10
	v_or3_b32 v4, v156, v157, v4
	v_lshl_or_b32 v5, v9, 24, v4
	ds_write_b16 v68, v4 offset:65280
	v_add_u32_e32 v4, 0x10010, v68
	ds_write_b16_d16_hi v4, v5
	v_pk_fma_f32 v[4:5], v[2:3], v[8:9], 0.5 op_sel_hi:[1,0,0]
	v_pk_add_f32 v[0:1], v[56:57], v[0:1]
	v_cvt_u32_f32_e32 v4, v4
	v_cvt_u32_f32_e32 v5, v5
	v_cvt_pk_bf16_f32 v0, v0, v1
	ds_write_b16 v58, v0 offset:31008
	ds_write_b16_d16_hi v58, v0 offset:31280
	v_lshlrev_b32_e32 v0, 8, v4
	v_add_u32_e32 v2, 0, v53
	v_or3_b32 v0, v163, v179, v0
	v_add_u32_e32 v2, 0x7920, v2
	v_lshl_or_b32 v1, v5, 24, v0
	ds_write_b16 v2, v0 offset:34816
	ds_write_b16_d16_hi v2, v1 offset:35088
	s_cmp_eq_u32 s24, 0x100
	s_cbranch_scc0 .Llru_nopre
	s_add_i32 s78, s69, s24
	s_cmpk_lt_i32 s78, 0x800
	s_cbranch_scc0 .Llru_nopre
	v_lshlrev_b32_e32 v250, 3, v202
	v_and_b32_e32 v250, 0x78, v250
	v_or_b32_e32 v250, s38, v250
	v_lshlrev_b32_e32 v250, 2, v250
	s_add_u32 s84, s20, 0x2000
	s_addc_u32 s85, s21, 0
	s_add_u32 s86, s20, 0x4000
	s_addc_u32 s87, s21, 0
	s_add_u32 s88, s20, 0x6000
	s_addc_u32 s89, s21, 0
	s_ashr_i32 s79, s78, 4
	v_and_b32_e32 v251, -4, v94
	v_lshl_add_u32 v251, s79, 7, v251
	v_add_u32_e32 v251, 4, v251
	global_load_dwordx4 v[12:15], v250, s[84:85]
	global_load_dwordx4 v[0:3], v250, s[84:85] offset:16
	global_load_dwordx4 v[32:35], v250, s[86:87]
	global_load_dwordx4 v[24:27], v250, s[86:87] offset:16
	global_load_dwordx4 v[16:19], v250, s[88:89]
	global_load_dwordx4 v[4:7], v250, s[88:89] offset:16
	global_load_dwordx4 v[28:31], v250, s[20:21] offset:16
	global_load_dwordx4 v[8:11], v250, s[22:23] offset:16
	global_load_dwordx4 v[36:39], v250, s[20:21]
	global_load_dwordx4 v[20:23], v250, s[22:23]
	global_load_dwordx4 v[40:43], v[248:249], off offset:-1024
	global_load_dwordx4 v[44:47], v[248:249], off offset:-512
	global_load_dwordx4 v[48:51], v[248:249], off
	global_load_dwordx4 v[52:55], v[248:249], off offset:512
	global_load_dwordx4 v[56:59], v[248:249], off offset:1024
	global_load_dwordx4 v[60:63], v[248:249], off offset:1536
	v_mov_b32_e32 v64, 0
	v_mov_b32_e32 v65, 0
	v_mov_b32_e32 v66, 0
	v_mov_b32_e32 v67, 0
	v_cmp_gt_u32_e32 vcc, s65, v251
	s_and_saveexec_b64 s[80:81], vcc
	global_load_dwordx4 v[64:67], v[248:249], off offset:2048
	s_or_b64 exec, exec, s[80:81]
	s_mov_b32 s71, 1

; DI void phase_carry(const Params& p) {
;     const int tid = threadIdx.x;
;     if (tid >= 64) return;
;     const f32x2* AGG = (const f32x2*)(p.ws + WS_AGG); float* CAR = (float*)(p.ws + WS_CAR);
;     for (int w = blockIdx.x; w < 64; w += gridDim.x) {
;         const int id = w * 64 + tid, d = id >> 11, ch = id & 2047;
;         const f32x2* ag = AGG + (size_t)d * 128 * 2048 + ch; float* car = CAR + (size_t)d * 128 * 2048 + ch;
;         float cin = 0.f;
;         for (int b = 0; b < 4; ++b) {
;             f32x2 v[32];
; #pragma unroll
;             for (int u = 0; u < 32; ++u) { const int k = b * 32 + u, cc = d == 0 ? k : 127 - k; v[u] = ag[(size_t)cc * 2048]; }
; #pragma unroll
;             for (int u = 0; u < 32; ++u) { const int k = b * 32 + u, cc = d == 0 ? k : 127 - k; car[(size_t)cc * 2048] = cin; cin = fmaf(v[u][0], cin, v[u][1]); }
;         }
;     }
.LBB0_316:
	s_waitcnt lgkmcnt(0)
	s_cmp_lt_i32 s8, 4
	s_cselect_b64 s[4:5], -1, 0
	s_cmp_gt_i32 s9, 3
	s_cselect_b64 s[6:7], -1, 0
	s_and_b64 s[6:7], s[4:5], s[6:7]
	v_cmp_gt_u32_e32 vcc, 64, v202
	s_mov_b64 s[10:11], s[6:7]
	s_waitcnt vmcnt(0)
	v_mov_b32_e32 v1, s9
	s_and_saveexec_b64 s[6:7], s[10:11]
	s_cbranch_execz .LBB0_324
	s_cmp_gt_i32 s2, 63
	s_cbranch_scc1 .LBB0_323
	s_load_dwordx2 s[10:11], s[0:1], 0x80
	s_mov_b32 s87, s2
.Lp3_pass:
	v_and_b32_e32 v0, 63, v202
	v_lshrrev_b32_e32 v4, 6, v202
	s_lshr_b32 s12, s87, 5
	s_and_b32 s13, s87, 31
	s_lshl_b32 s13, s13, 6
	s_nop 1
	v_readfirstlane_b32 s14, v4
	v_add_u32_e32 v0, s13, v0
	s_nop 3
	s_lshl_b32 s15, s14, 4
	s_sub_i32 s16, 0x7f, s15
	s_mov_b32 s17, 0x4000
	s_mov_b32 s18, 0xffffc000
	s_mov_b32 s19, 0x2000
	s_mov_b32 s86, 0xffffe000
	s_cmp_eq_u32 s12, 0
	s_cselect_b32 s15, s15, s16
	s_cselect_b32 s17, s17, s18
	s_cselect_b32 s18, s19, s86
	s_lshl_b32 s19, s12, 7
	s_add_i32 s15, s15, s19
	s_lshl_b32 s19, s15, 14
	s_lshl_b32 s15, s15, 13
	v_lshl_add_u32 v2, v0, 3, s19
	v_lshl_add_u32 v3, v0, 2, s15
	s_waitcnt lgkmcnt(0)
	s_add_u32 s82, s10, 0x1ba00000
	s_addc_u32 s83, s11, 0
	s_add_u32 s84, s10, 0x1c200000
	s_addc_u32 s85, s11, 0
	global_load_dwordx2 v[10:11], v2, s[82:83]
	v_add_u32_e32 v2, s17, v2
	global_load_dwordx2 v[12:13], v2, s[82:83]
	v_add_u32_e32 v2, s17, v2
	global_load_dwordx2 v[14:15], v2, s[82:83]
	v_add_u32_e32 v2, s17, v2
	global_load_dwordx2 v[16:17], v2, s[82:83]
	v_add_u32_e32 v2, s17, v2
	global_load_dwordx2 v[18:19], v2, s[82:83]
	v_add_u32_e32 v2, s17, v2
	global_load_dwordx2 v[20:21], v2, s[82:83]
	v_add_u32_e32 v2, s17, v2
	global_load_dwordx2 v[22:23], v2, s[82:83]
	v_add_u32_e32 v2, s17, v2
	global_load_dwordx2 v[24:25], v2, s[82:83]
	v_add_u32_e32 v2, s17, v2
	global_load_dwordx2 v[26:27], v2, s[82:83]
	v_add_u32_e32 v2, s17, v2
	global_load_dwordx2 v[28:29], v2, s[82:83]
	v_add_u32_e32 v2, s17, v2
	global_load_dwordx2 v[30:31], v2, s[82:83]
	v_add_u32_e32 v2, s17, v2
	global_load_dwordx2 v[32:33], v2, s[82:83]
	v_add_u32_e32 v2, s17, v2
	global_load_dwordx2 v[34:35], v2, s[82:83]
	v_add_u32_e32 v2, s17, v2
	global_load_dwordx2 v[36:37], v2, s[82:83]
	v_add_u32_e32 v2, s17, v2
	global_load_dwordx2 v[38:39], v2, s[82:83]
	v_add_u32_e32 v2, s17, v2
	global_load_dwordx2 v[40:41], v2, s[82:83]
	v_mov_b32_e32 v6, 1.0
	v_mov_b32_e32 v7, 0
	s_waitcnt vmcnt(15)
	v_fma_f32 v7, v10, v7, v11
	v_mul_f32_e32 v6, v6, v10
	s_waitcnt vmcnt(14)
	v_fma_f32 v7, v12, v7, v13
	v_mul_f32_e32 v6, v6, v12
	s_waitcnt vmcnt(13)
	v_fma_f32 v7, v14, v7, v15
	v_mul_f32_e32 v6, v6, v14
	s_waitcnt vmcnt(12)
	v_fma_f32 v7, v16, v7, v17
	v_mul_f32_e32 v6, v6, v16
	s_waitcnt vmcnt(11)
	v_fma_f32 v7, v18, v7, v19
	v_mul_f32_e32 v6, v6, v18
	s_waitcnt vmcnt(10)
	v_fma_f32 v7, v20, v7, v21
	v_mul_f32_e32 v6, v6, v20
	s_waitcnt vmcnt(9)
	v_fma_f32 v7, v22, v7, v23
	v_mul_f32_e32 v6, v6, v22
	s_waitcnt vmcnt(8)
	v_fma_f32 v7, v24, v7, v25
	v_mul_f32_e32 v6, v6, v24
	s_waitcnt vmcnt(7)
	v_fma_f32 v7, v26, v7, v27
	v_mul_f32_e32 v6, v6, v26
	s_waitcnt vmcnt(6)
	v_fma_f32 v7, v28, v7, v29
	v_mul_f32_e32 v6, v6, v28
	s_waitcnt vmcnt(5)
	v_fma_f32 v7, v30, v7, v31
	v_mul_f32_e32 v6, v6, v30
	s_waitcnt vmcnt(4)
	v_fma_f32 v7, v32, v7, v33
	v_mul_f32_e32 v6, v6, v32
	s_waitcnt vmcnt(3)
	v_fma_f32 v7, v34, v7, v35
	v_mul_f32_e32 v6, v6, v34
	s_waitcnt vmcnt(2)
	v_fma_f32 v7, v36, v7, v37
	v_mul_f32_e32 v6, v6, v36
	s_waitcnt vmcnt(1)
	v_fma_f32 v7, v38, v7, v39
	v_mul_f32_e32 v6, v6, v38
	s_waitcnt vmcnt(0)
	v_fma_f32 v7, v40, v7, v41
	v_mul_f32_e32 v6, v6, v40
	v_lshlrev_b32_e32 v5, 3, v202
	ds_write_b64 v5, v[6:7]
	s_waitcnt lgkmcnt(0)
	s_barrier
	v_and_b32_e32 v8, 63, v202
	v_lshlrev_b32_e32 v8, 3, v8
	ds_read_b64 v[50:51], v8
	ds_read_b64 v[52:53], v8 offset:512
	ds_read_b64 v[54:55], v8 offset:1024
	ds_read_b64 v[56:57], v8 offset:1536
	ds_read_b64 v[58:59], v8 offset:2048
	ds_read_b64 v[60:61], v8 offset:2560
	ds_read_b64 v[62:63], v8 offset:3072
	v_mov_b32_e32 v9, 0
	s_waitcnt lgkmcnt(0)
	s_cmp_gt_u32 s14, 0
	s_cbranch_scc0 .Lp3_c0_done
	v_fma_f32 v9, v50, v9, v51
	s_cmp_gt_u32 s14, 1
	s_cbranch_scc0 .Lp3_c0_done
	v_fma_f32 v9, v52, v9, v53
	s_cmp_gt_u32 s14, 2
	s_cbranch_scc0 .Lp3_c0_done
	v_fma_f32 v9, v54, v9, v55
	s_cmp_gt_u32 s14, 3
	s_cbranch_scc0 .Lp3_c0_done
	v_fma_f32 v9, v56, v9, v57
	s_cmp_gt_u32 s14, 4
	s_cbranch_scc0 .Lp3_c0_done
	v_fma_f32 v9, v58, v9, v59
	s_cmp_gt_u32 s14, 5
	s_cbranch_scc0 .Lp3_c0_done
	v_fma_f32 v9, v60, v9, v61
	s_cmp_gt_u32 s14, 6
	s_cbranch_scc0 .Lp3_c0_done
	v_fma_f32 v9, v62, v9, v63
.Lp3_c0_done:
	global_store_dword v3, v9, s[84:85]
	v_fma_f32 v9, v10, v9, v11
	v_add_u32_e32 v3, s18, v3
	global_store_dword v3, v9, s[84:85]
	v_fma_f32 v9, v12, v9, v13
	v_add_u32_e32 v3, s18, v3
	global_store_dword v3, v9, s[84:85]
	v_fma_f32 v9, v14, v9, v15
	v_add_u32_e32 v3, s18, v3
	global_store_dword v3, v9, s[84:85]
	v_fma_f32 v9, v16, v9, v17
	v_add_u32_e32 v3, s18, v3
	global_store_dword v3, v9, s[84:85]
	v_fma_f32 v9, v18, v9, v19
	v_add_u32_e32 v3, s18, v3
	global_store_dword v3, v9, s[84:85]
	v_fma_f32 v9, v20, v9, v21
	v_add_u32_e32 v3, s18, v3
	global_store_dword v3, v9, s[84:85]
	v_fma_f32 v9, v22, v9, v23
	v_add_u32_e32 v3, s18, v3
	global_store_dword v3, v9, s[84:85]
	v_fma_f32 v9, v24, v9, v25
	v_add_u32_e32 v3, s18, v3
	global_store_dword v3, v9, s[84:85]
	v_fma_f32 v9, v26, v9, v27
	v_add_u32_e32 v3, s18, v3
	global_store_dword v3, v9, s[84:85]
	v_fma_f32 v9, v28, v9, v29
	v_add_u32_e32 v3, s18, v3
	global_store_dword v3, v9, s[84:85]
	v_fma_f32 v9, v30, v9, v31
	v_add_u32_e32 v3, s18, v3
	global_store_dword v3, v9, s[84:85]
	v_fma_f32 v9, v32, v9, v33
	v_add_u32_e32 v3, s18, v3
	global_store_dword v3, v9, s[84:85]
	v_fma_f32 v9, v34, v9, v35
	v_add_u32_e32 v3, s18, v3
	global_store_dword v3, v9, s[84:85]
	v_fma_f32 v9, v36, v9, v37
	v_add_u32_e32 v3, s18, v3
	global_store_dword v3, v9, s[84:85]
	v_fma_f32 v9, v38, v9, v39
	v_add_u32_e32 v3, s18, v3
	global_store_dword v3, v9, s[84:85]
	v_fma_f32 v9, v40, v9, v41
	s_add_i32 s87, s87, s24
	s_cmp_lt_i32 s87, 64
	s_cbranch_scc0 .Lp3_done
	s_barrier
	s_branch .Lp3_pass
.Lp3_done:
	s_load_dword s9, s[0:1], 0xcc
